# QKV and up-proj phase prologues: the 4 row-statistics loads go to spare registers and their reduce + rsqrt + LDS write runs after the first tile's LDS-DMA loads are issued (was: vmcnt(0) wait before a
# speedup vs baseline: 1.0092x; 1.0005x over previous
; #define PG8_LAS __attribute__((address_space(3)))
; #define PG8_STAGE(bufoff, gbase, voff) do { _Pragma("unroll") for (int _i = 0; _i < 2; ++_i) \
;         __builtin_amdgcn_global_load_lds((const unsigned*)((const char*)(gbase) + (voff)[_i]), (PG8_LAS unsigned*)(lds + (bufoff) + ldsw + _i * 8192), 16, 0, 0); } while (0)
; #define PG8_WAIT_V(n) asm volatile("s_waitcnt vmcnt(" #n ")" ::: "memory")
; #define PG8_BAR __builtin_amdgcn_s_barrier()
; __device__ __forceinline__ void prep_rstd(PG8_LAS unsigned char* lds, const float* ss, int tid, int pm) {
;     PG8_LAS float* RS = (PG8_LAS float*)(lds + LDS_RS_OFF);
;     const int row = tid >> 1, h = tid & 1; const f32x4* p = (const f32x4*)(ss + (size_t)(pm * BM + row) * 32 + 16 * h);
;     f32x4 a = p[0] + p[1]; const f32x4 b = p[2] + p[3]; a += b; float t = (a[0] + a[1]) + (a[2] + a[3]);
; template <class Epi, class Sched, bool ALIGN_EPI = false, bool SP2 = false>
; __device__ __forceinline__ void gemm_phase(PG8_LAS unsigned char* lds, const Gemm g, const Sched& S, const Epi& E, int wave_s) {
;     ...
;     const char* cA = (const char*)g.A + (size_t)cur.pm * tstepA + (size_t)(cur.pn / g.npg) * (size_t)(K * 2); const char* cB = (const char*)g.Bt + (size_t)cur.pn * tstepB;
;     S.a_ready(cur);
;     if constexpr (SP2) {
;         PG8_STAGE(PG8_SB(0, 0), cB, voffB); PG8_STAGE(PG8_SB(0, 1), cB + hstepB, voffB); PG8_STAGE(PG8_SA(0, 0), cA, voffA); PG8_STAGE(PG8_SA(0, 1), cA + hstepA, voffA);
;         if (wr == 1) PG8_BAR;
;         PG8_WAIT_V(2); PG8_BAR;
.LBB0_398:
	s_and_b64 vcc, exec, s[2:3]
	s_cbranch_vccz .LBB0_678
	s_lshl_b32 s4, s52, 20
	s_mov_b32 s5, s51
	v_writelane_b32 v255, s4, 43
	s_mov_b64 s[2:3], s[80:81]
	v_mbcnt_lo_u32_b32 v10, -1, 0
	v_mbcnt_hi_u32_b32 v10, -1, v10
	s_mov_b32 s93, s51
	v_writelane_b32 v255, s5, 44
	v_or_b32_e32 v1, s55, v10
	v_readlane_b32 s4, v255, 7
	v_readlane_b32 s5, v255, 8
	s_andn2_b64 vcc, exec, s[4:5]
	v_readfirstlane_b32 s6, v1
	s_mov_b64 s[86:87], 0x1000
	s_cbranch_vccnz .LBB0_419
	s_load_dwordx2 s[4:5], s[2:3], 0x80
	v_readlane_b32 s2, v255, 43
	v_readlane_b32 s3, v255, 44
	v_ashrrev_i32_e32 v2, 1, v1
	v_readlane_b32 s7, v255, 13
	s_lshl_b64 s[2:3], s[2:3], 2
	s_waitcnt lgkmcnt(0)
	s_add_u32 s2, s4, s2
	v_add_u32_e32 v4, s7, v2
	v_ashrrev_i32_e32 v5, 31, v4
	v_and_b32_e32 v11, 1, v10
	s_addc_u32 s3, s5, s3
	v_lshlrev_b64 v[4:5], 7, v[4:5]
	v_lshl_add_u64 v[4:5], s[2:3], 0, v[4:5]
	v_lshlrev_b32_e32 v6, 6, v11
	v_mov_b32_e32 v7, v0
	v_lshl_add_u64 v[8:9], v[4:5], 0, v[6:7]
	global_load_dwordx4 v[220:223], v[8:9], off
	global_load_dwordx4 v[224:227], v[8:9], off offset:16
	global_load_dwordx4 v[228:231], v[8:9], off offset:32
	global_load_dwordx4 v[240:243], v[8:9], off offset:48
	v_ashrrev_i32_e32 v3, 31, v1
	v_lshrrev_b32_e32 v3, 26, v3
	v_lshlrev_b32_e32 v2, 4, v1
	v_add_u32_e32 v3, v1, v3
	v_bfe_i32 v1, v1, 27, 1
	v_lshrrev_b32_e32 v1, 22, v1
	v_add_u32_e32 v1, v2, v1
	v_and_b32_e32 v1, 0xfffffc00, v1
	v_sub_u32_e32 v1, v2, v1
	v_ashrrev_i32_e32 v11, 6, v3
	v_lshrrev_b32_e32 v3, 4, v1
	v_bitop3_b32 v1, v3, v1, 32 bitop3:0x6c
	v_ashrrev_i32_e32 v4, 31, v1
	v_lshrrev_b32_e32 v4, 26, v4
	s_add_u32 s16, s4, 0x14400000
	v_add_u32_e32 v4, v1, v4
	s_addc_u32 s17, s5, 0
	s_mul_i32 s3, s92, 0xa00000
	v_lshlrev_b32_e32 v3, 3, v11
	v_ashrrev_i32_e32 v12, 6, v4
	v_and_b32_e32 v4, 0xc0, v4
	s_mul_hi_u32 s2, s92, 0xa00000
	s_add_u32 s3, s4, s3
	v_and_b32_e32 v3, -16, v3
	v_sub_u32_e32 v1, v1, v4
	s_addc_u32 s2, s5, s2
	v_add_u32_e32 v3, v12, v3
	v_ashrrev_i16_sdwa v1, v237, sext(v1) dst_sel:DWORD dst_unused:UNUSED_PAD src0_sel:DWORD src1_sel:BYTE_0
	s_add_u32 s22, s3, 0x1400000
	v_lshlrev_b32_e32 v5, 5, v11
	v_bfe_i32 v13, v1, 0, 16
	v_lshlrev_b32_e32 v1, 1, v3
	v_lshrrev_b32_e32 v4, 2, v3
	v_and_b32_e32 v6, 3, v12
	s_mov_b32 s3, 0xfffe0
	v_and_b32_e32 v5, 32, v5
	v_and_b32_e32 v1, 24, v1
	v_and_b32_e32 v4, 4, v4
	v_and_or_b32 v6, v3, s3, v6
	v_or3_b32 v1, v6, v4, v1
	v_add_lshl_u32 v4, v5, v13, 1
	v_lshl_add_u32 v132, v1, 12, v4
	v_add_u32_e32 v1, 0x2000, v2
	v_ashrrev_i32_e32 v2, 31, v1
	v_lshrrev_b32_e32 v2, 22, v2
	v_add_u32_e32 v2, v1, v2
	v_ashrrev_i32_e32 v14, 10, v2
	v_mul_i32_i24_e32 v2, 0x400, v14
	v_sub_u32_e32 v1, v1, v2
	v_lshrrev_b32_e32 v2, 4, v1
	v_bitop3_b32 v1, v2, v1, 32 bitop3:0x6c
	v_lshl_add_u32 v130, v3, 12, v4
	v_ashrrev_i32_e32 v3, 31, v1
	v_lshrrev_b32_e32 v3, 26, v3
	v_lshlrev_b32_e32 v2, 3, v14
	v_add_u32_e32 v3, v1, v3
	v_and_b32_e32 v2, -16, v2
	v_ashrrev_i32_e32 v15, 6, v3
	v_add_u32_e32 v2, v15, v2
	v_and_b32_e32 v5, 3, v15
	s_addc_u32 s23, s2, 0
	v_and_or_b32 v5, v2, s3, v5
	s_ashr_i32 s3, s6, 6
	s_ashr_i32 s2, s6, 8
	s_lshl_b32 s34, s3, 10
	v_readlane_b32 s8, v255, 18
	v_and_b32_e32 v3, 0xc0, v3
	v_readlane_b32 s9, v255, 19
	s_add_u32 s30, s22, s8
	v_sub_u32_e32 v1, v1, v3
	s_addc_u32 s31, s23, s9
	s_add_i32 s35, s34, 0
	v_ashrrev_i16_sdwa v1, v237, sext(v1) dst_sel:DWORD dst_unused:UNUSED_PAD src0_sel:DWORD src1_sel:BYTE_0
	s_add_i32 m0, s35, 0x10000
	v_lshlrev_b32_e32 v4, 5, v14
	v_bfe_i32 v16, v1, 0, 16
	v_lshlrev_b32_e32 v1, 1, v2
	v_lshrrev_b32_e32 v3, 2, v2
	s_waitcnt lgkmcnt(0)
	s_waitcnt lgkmcnt(0)
	s_barrier
	global_load_lds_dwordx4 v132, s[30:31]
	s_add_i32 m0, s35, 0x12000
	v_readlane_b32 s8, v255, 16
	v_and_b32_e32 v4, 32, v4
	v_and_b32_e32 v1, 24, v1
	v_and_b32_e32 v3, 4, v3
	v_readlane_b32 s9, v255, 17
	s_add_u32 s40, s16, s8
	v_or3_b32 v1, v5, v3, v1
	v_add_lshl_u32 v3, v4, v16, 1
	s_addc_u32 s41, s17, s9
	v_lshl_add_u32 v136, v1, 12, v3
	s_add_u32 s8, s30, 0x80000
	global_load_lds_dwordx4 v136, s[30:31]
	s_addc_u32 s9, s31, 0
	s_add_i32 m0, s35, 0x14000
	s_add_i32 s36, s35, 0x2000
	global_load_lds_dwordx4 v132, s[8:9]
	s_add_i32 m0, s35, 0x16000
	v_lshl_add_u32 v134, v2, 12, v3
	global_load_lds_dwordx4 v136, s[8:9]
	s_mov_b32 m0, s35
	s_add_u32 s8, s40, 0x80000
	global_load_lds_dwordx4 v130, s[40:41]
	s_mov_b32 m0, s36
	s_addc_u32 s9, s41, 0
	s_add_i32 s37, s35, 0x4000
	global_load_lds_dwordx4 v134, s[40:41]
	s_mov_b32 m0, s37
	s_add_i32 s42, s35, 0x6000
	global_load_lds_dwordx4 v130, s[8:9]
	s_mov_b32 m0, s42
	v_mov_b32_e32 v133, v0
	global_load_lds_dwordx4 v134, s[8:9]
	v_mov_b32_e32 v137, v0
	v_mov_b32_e32 v131, v0
	v_mov_b32_e32 v135, v0
	s_cmp_eq_u32 s2, 1
	v_lshl_add_u64 v[8:9], s[30:31], 0, v[132:133]
	v_lshl_add_u64 v[6:7], s[30:31], 0, v[136:137]
	v_lshl_add_u64 v[2:3], s[40:41], 0, v[130:131]
	s_cselect_b64 s[8:9], -1, 0
	s_cmp_lg_u32 s2, 1
	v_lshl_add_u64 v[4:5], s[40:41], 0, v[134:135]
	s_cbranch_scc1 .LBB0_404
	s_barrier
; __device__ __forceinline__ float sum_x1(float s) { return s + DPP_MOVF(s, 0xB1); }
; __device__ __forceinline__ void prep_rstd(PG8_LAS unsigned char* lds, const float* ss, int tid, int pm) {
;     ...
;     f32x4 a = p[0] + p[1]; const f32x4 b = p[2] + p[3]; a += b; float t = (a[0] + a[1]) + (a[2] + a[3]);
;     t = sum_x1(t);
;     if (h == 0) RS[row] = __builtin_amdgcn_rsqf(t * (1.0f / 2048.0f) + RMS_EPS);
;     asm volatile("s_waitcnt lgkmcnt(0)" ::: "memory"); __syncthreads();
.LBB0_404:
	s_add_u32 s10, s4, 0x18400000
	s_addc_u32 s11, s5, 0
	s_lshl_b32 s3, s3, 5
	s_and_b32 s44, s3, 0x60
	s_add_i32 m0, s35, 0x18000
	v_lshl_add_u64 v[8:9], v[8:9], 0, s[60:61]
	s_lshl_b32 s43, s2, 6
	s_lshl_b32 s7, s2, 13
	s_lshl_b32 s3, s44, 7
	global_load_lds_dwordx4 v[8:9], off
	v_lshl_add_u64 v[6:7], v[6:7], 0, s[60:61]
	s_add_i32 m0, s35, 0x1a000
	s_add_i32 s45, s35, 0x8000
	s_add_i32 s46, s35, 0xa000
	global_load_lds_dwordx4 v[6:7], off
	v_lshl_add_u64 v[2:3], v[2:3], 0, s[60:61]
	s_mov_b32 m0, s45
	s_add_u32 s4, s30, 0x80080
	global_load_lds_dwordx4 v[2:3], off
	v_lshl_add_u64 v[2:3], v[4:5], 0, s[60:61]
	s_mov_b32 m0, s46
	s_addc_u32 s5, s31, 0
	global_load_lds_dwordx4 v[2:3], off
	s_add_i32 m0, s35, 0x1c000
	v_lshl_add_u64 v[2:3], s[4:5], 0, v[132:133]
	global_load_lds_dwordx4 v[2:3], off
	v_lshl_add_u64 v[2:3], s[4:5], 0, v[136:137]
	s_add_i32 m0, s35, 0x1e000
	v_bfe_u32 v146, v10, 4, 2
	global_load_lds_dwordx4 v[2:3], off
	s_waitcnt vmcnt(14)
	v_pk_add_f32 v[222:223], v[222:223], v[226:227]
	v_pk_add_f32 v[220:221], v[220:221], v[224:225]
	v_pk_add_f32 v[244:245], v[230:231], v[242:243]
	v_pk_add_f32 v[246:247], v[228:229], v[240:241]
	v_pk_add_f32 v[222:223], v[222:223], v[244:245]
	v_pk_add_f32 v[220:221], v[220:221], v[246:247]
	v_mbcnt_lo_u32_b32 v251, -1, 0
	v_add_f32_e32 v248, v220, v221
	v_add_f32_e32 v249, v222, v223
	v_mbcnt_hi_u32_b32 v251, -1, v251
	v_add_f32_e32 v248, v248, v249
	v_and_b32_e32 v252, 1, v251
	v_or_b32_e32 v251, s55, v251
	v_mov_b32_dpp v249, v248 quad_perm:[1,0,3,2] row_mask:0xf bank_mask:0xf bound_ctrl:1
	v_cmp_eq_u32_e64 s[12:13], 0, v252
	v_ashrrev_i32_e32 v251, 1, v251
	s_and_saveexec_b64 s[12:13], s[12:13]
	s_cbranch_execz .Lrs_q
	v_add_f32_e32 v248, v248, v249
	v_fmamk_f32 v248, v248, 0x3a000000, v250
	v_rsq_f32_e32 v248, v248
	v_lshl_add_u32 v251, v251, 2, 0
	v_add_u32_e32 v251, 0x22100, v251
	ds_write_b32 v251, v248
.Lrs_q:
	s_or_b64 exec, exec, s[12:13]
	s_waitcnt vmcnt(8)
	s_barrier
	v_and_b32_e32 v1, 15, v10
	v_lshlrev_b32_e32 v2, 4, v146
	v_lshlrev_b32_e32 v3, 2, v10
	v_lshl_or_b32 v2, v1, 6, v2
	v_and_b32_e32 v3, 32, v3
	v_bitop3_b32 v4, v2, s7, v3 bitop3:0xde
	v_bitop3_b32 v147, v2, s3, v3 bitop3:0xde
	v_lshlrev_b32_e32 v2, 15, v11
	v_and_b32_e32 v2, 0xffff0000, v2
	v_lshl_add_u32 v2, v12, 12, v2
	v_and_b32_e32 v3, 1, v11
	v_lshl_or_b32 v2, v3, 6, v2
	v_lshl_add_u32 v138, v13, 1, v2
	v_lshlrev_b32_e32 v2, 15, v14
	s_cmpk_lt_u32 s6, 0x100
	v_and_b32_e32 v2, 0xffff0000, v2
	s_waitcnt vmcnt(6)
	s_cselect_b64 s[12:13], -1, 0
	s_lshl_b32 s2, s2, 8
	v_lshl_add_u32 v2, v15, 12, v2
	v_and_b32_e32 v3, 1, v14
	s_add_i32 s90, s2, 0
	v_lshl_or_b32 v2, v3, 6, v2
	v_readlane_b32 s2, v255, 14
	s_add_i32 s47, s90, 0x22100
	s_add_i32 s50, s90, 0x22140
	s_add_i32 s77, s90, 0x22180
	s_add_i32 s80, s90, 0x221c0
	s_add_i32 s81, s90, 0x22300
	s_add_i32 s88, s90, 0x22340
	s_add_i32 s89, s90, 0x22380
	s_add_i32 s90, s90, 0x223c0
	v_mov_b32_e32 v139, v0
	v_lshl_add_u32 v140, v16, 1, v2
	v_mov_b32_e32 v141, v0
	s_mov_b32 s91, 0
	v_add_u32_e32 v148, 0, v4
	v_readlane_b32 s84, v255, 12
	s_mov_b32 s85, s2
	s_barrier
	v_readlane_b32 s3, v255, 15
	s_branch .LBB0_407

; #define PG8_LAS __attribute__((address_space(3)))
; #define PG8_STAGE(bufoff, gbase, voff) do { _Pragma("unroll") for (int _i = 0; _i < 2; ++_i) \
;         __builtin_amdgcn_global_load_lds((const unsigned*)((const char*)(gbase) + (voff)[_i]), (PG8_LAS unsigned*)(lds + (bufoff) + ldsw + _i * 8192), 16, 0, 0); } while (0)
; #define PG8_WAIT_V(n) asm volatile("s_waitcnt vmcnt(" #n ")" ::: "memory")
; #define PG8_BAR __builtin_amdgcn_s_barrier()
; __device__ __forceinline__ void prep_rstd(PG8_LAS unsigned char* lds, const float* ss, int tid, int pm) {
;     PG8_LAS float* RS = (PG8_LAS float*)(lds + LDS_RS_OFF);
;     const int row = tid >> 1, h = tid & 1; const f32x4* p = (const f32x4*)(ss + (size_t)(pm * BM + row) * 32 + 16 * h);
;     f32x4 a = p[0] + p[1]; const f32x4 b = p[2] + p[3]; a += b; float t = (a[0] + a[1]) + (a[2] + a[3]);
; template <class Epi, class Sched, bool ALIGN_EPI = false, bool SP2 = false>
; __device__ __forceinline__ void gemm_phase(PG8_LAS unsigned char* lds, const Gemm g, const Sched& S, const Epi& E, int wave_s) {
;     ...
;     const char* cA = (const char*)g.A + (size_t)cur.pm * tstepA + (size_t)(cur.pn / g.npg) * (size_t)(K * 2); const char* cB = (const char*)g.Bt + (size_t)cur.pn * tstepB;
;     S.a_ready(cur);
;     if constexpr (SP2) {
;         PG8_STAGE(PG8_SB(0, 0), cB, voffB); PG8_STAGE(PG8_SB(0, 1), cB + hstepB, voffB); PG8_STAGE(PG8_SA(0, 0), cA, voffA); PG8_STAGE(PG8_SA(0, 1), cA + hstepA, voffA);
;         if (wr == 1) PG8_BAR;
;         PG8_WAIT_V(2); PG8_BAR;
.LBB0_678:
	s_mov_b64 s[2:3], s[80:81]
	v_readlane_b32 s4, v255, 9
	v_mbcnt_lo_u32_b32 v10, -1, 0
	v_mbcnt_hi_u32_b32 v10, -1, v10
	v_readlane_b32 s5, v255, 10
	v_or_b32_e32 v1, s55, v10
	s_mul_hi_u32 s11, s52, 0x2c00
	s_mul_i32 s10, s52, 0x2c00
	s_mul_hi_u32 s13, s52, 0x8400
	s_mul_i32 s12, s52, 0x8400
	s_andn2_b64 vcc, exec, s[4:5]
	v_readfirstlane_b32 s20, v1
	s_cbranch_vccnz .LBB0_710
	s_load_dwordx2 s[8:9], s[2:3], 0x80
	v_readlane_b32 s4, v255, 43
	v_readlane_b32 s5, v255, 44
	v_ashrrev_i32_e32 v2, 1, v1
	v_readlane_b32 s6, v255, 31
	s_lshl_b64 s[4:5], s[4:5], 2
	s_waitcnt lgkmcnt(0)
	s_add_u32 s4, s8, s4
	v_add_u32_e32 v4, s6, v2
	v_ashrrev_i32_e32 v5, 31, v4
	v_and_b32_e32 v11, 1, v10
	s_addc_u32 s5, s9, s5
	v_lshlrev_b64 v[4:5], 7, v[4:5]
	v_lshl_add_u64 v[4:5], s[4:5], 0, v[4:5]
	v_lshlrev_b32_e32 v6, 6, v11
	v_mov_b32_e32 v7, v0
	v_lshl_add_u64 v[4:5], v[4:5], 0, v[6:7]
	s_mov_b64 s[4:5], 0x200000
	v_lshl_add_u64 v[8:9], v[4:5], 0, s[4:5]
	s_mov_b32 s4, 0x200000
	v_add_co_u32_e32 v4, vcc, s4, v4
	s_nop 1
	v_addc_co_u32_e32 v5, vcc, 0, v5, vcc
	global_load_dwordx4 v[204:207], v[4:5], off
	s_nop 0
	global_load_dwordx4 v[208:211], v[8:9], off offset:16
	global_load_dwordx4 v[212:215], v[8:9], off offset:32
	global_load_dwordx4 v[216:219], v[8:9], off offset:48
	v_ashrrev_i32_e32 v3, 31, v1
	v_lshrrev_b32_e32 v3, 26, v3
	v_lshlrev_b32_e32 v2, 4, v1
	v_add_u32_e32 v3, v1, v3
	v_bfe_i32 v1, v1, 27, 1
	v_lshrrev_b32_e32 v1, 22, v1
	v_add_u32_e32 v1, v2, v1
	v_and_b32_e32 v1, 0xfffffc00, v1
	v_sub_u32_e32 v1, v2, v1
	v_lshrrev_b32_e32 v4, 4, v1
	v_bitop3_b32 v1, v4, v1, 32 bitop3:0x6c
	v_ashrrev_i32_e32 v5, 31, v1
	s_add_u32 s16, s8, 0x14400000
	v_ashrrev_i32_e32 v3, 6, v3
	v_lshrrev_b32_e32 v5, 26, v5
	s_load_dwordx4 s[4:7], s[2:3], 0x60
	s_addc_u32 s17, s9, 0
	s_mul_i32 s3, s52, 0x2c00000
	v_lshlrev_b32_e32 v4, 3, v3
	v_add_u32_e32 v5, v1, v5
	s_mul_hi_u32 s2, s52, 0x2c00000
	s_add_u32 s3, s8, s3
	v_and_b32_e32 v4, -16, v4
	v_ashrrev_i32_e32 v6, 6, v5
	v_lshlrev_b32_e32 v3, 5, v3
	s_addc_u32 s2, s9, s2
	v_add_u32_e32 v12, v6, v4
	v_and_b32_e32 v11, 32, v3
	v_and_b32_e32 v3, 0xc0, v5
	s_add_u32 s22, s3, 0x3800000
	v_sub_u32_e32 v1, v1, v3
	v_lshlrev_b32_e32 v3, 1, v12
	v_lshrrev_b32_e32 v4, 2, v12
	v_and_b32_e32 v7, 3, v6
	s_mov_b32 s3, 0xfffe0
	v_ashrrev_i16_sdwa v1, v237, sext(v1) dst_sel:DWORD dst_unused:UNUSED_PAD src0_sel:DWORD src1_sel:BYTE_0
	v_and_b32_e32 v3, 24, v3
	v_and_b32_e32 v5, 4, v4
	v_and_or_b32 v7, v12, s3, v7
	v_bfe_i32 v13, v1, 0, 16
	v_or3_b32 v3, v7, v5, v3
	v_lshlrev_b32_e32 v5, 7, v12
	v_add_u32_e32 v1, v11, v13
	v_and_b32_e32 v15, 0x1800, v5
	v_add_u32_e32 v5, v1, v15
	v_lshlrev_b32_e32 v1, 1, v1
	v_lshl_add_u32 v238, v3, 12, v1
	v_add_u32_e32 v1, 0x2000, v2
	v_ashrrev_i32_e32 v2, 31, v1
	v_lshrrev_b32_e32 v2, 22, v2
	v_add_u32_e32 v2, v1, v2
	v_ashrrev_i32_e32 v2, 10, v2
	v_mul_i32_i24_e32 v3, 0x400, v2
	v_and_b32_e32 v14, 15, v6
	s_mov_b32 s14, 0x1fff0
	v_sub_u32_e32 v1, v1, v3
	v_and_or_b32 v4, v4, s14, v14
	v_lshrrev_b32_e32 v3, 4, v1
	v_lshlrev_b32_e32 v4, 15, v4
	v_bitop3_b32 v1, v3, v1, 32 bitop3:0x6c
	v_lshl_add_u32 v236, v5, 1, v4
	v_ashrrev_i32_e32 v4, 31, v1
	v_lshrrev_b32_e32 v4, 26, v4
	v_lshlrev_b32_e32 v3, 3, v2
	v_add_u32_e32 v4, v1, v4
	v_and_b32_e32 v3, -16, v3
	v_ashrrev_i32_e32 v5, 6, v4
	v_add_u32_e32 v16, v5, v3
	v_and_b32_e32 v3, 0xc0, v4
	s_addc_u32 s23, s2, 0
	s_ashr_i32 s2, s20, 6
	v_sub_u32_e32 v1, v1, v3
	v_lshrrev_b32_e32 v3, 2, v16
	v_and_b32_e32 v17, 15, v5
	v_lshlrev_b32_e32 v2, 5, v2
	v_and_b32_e32 v4, 4, v3
	v_and_or_b32 v3, v3, s14, v17
	s_ashr_i32 s34, s20, 8
	s_lshl_b32 s35, s2, 10
	v_readlane_b32 s14, v255, 36
	v_and_b32_e32 v2, 32, v2
	v_ashrrev_i16_sdwa v1, v237, sext(v1) dst_sel:DWORD dst_unused:UNUSED_PAD src0_sel:DWORD src1_sel:BYTE_0
	v_readlane_b32 s15, v255, 37
	s_add_u32 s40, s22, s14
	v_add_u32_sdwa v1, v2, sext(v1) dst_sel:DWORD dst_unused:UNUSED_PAD src0_sel:DWORD src1_sel:WORD_0
	v_lshlrev_b32_e32 v2, 1, v16
	v_and_b32_e32 v6, 3, v5
	s_addc_u32 s41, s23, s15
	s_add_i32 s36, s35, 0
	v_and_b32_e32 v2, 24, v2
	v_and_or_b32 v6, v16, s3, v6
	s_add_i32 m0, s36, 0x10000
	v_or3_b32 v2, v6, v4, v2
	v_lshlrev_b32_e32 v4, 7, v16
	s_waitcnt lgkmcnt(0)
	s_waitcnt lgkmcnt(0)
	s_barrier
	global_load_lds_dwordx4 v238, s[40:41]
	s_add_i32 m0, s36, 0x12000
	v_readlane_b32 s14, v255, 34
	v_and_b32_e32 v4, 0x1800, v4
	v_readlane_b32 s15, v255, 35
	s_add_u32 s30, s16, s14
	v_add_lshl_u32 v18, v1, v4, 1
	v_lshlrev_b32_e32 v1, 1, v1
	s_addc_u32 s31, s17, s15
	v_lshl_add_u32 v242, v2, 12, v1
	s_add_u32 s14, s40, 0x80000
	global_load_lds_dwordx4 v242, s[40:41]
	s_addc_u32 s15, s41, 0
	s_add_i32 m0, s36, 0x14000
	s_add_i32 s37, s36, 0x2000
	global_load_lds_dwordx4 v238, s[14:15]
	s_add_i32 m0, s36, 0x16000
	v_lshl_add_u32 v240, v3, 15, v18
	global_load_lds_dwordx4 v242, s[14:15]
	s_mov_b32 m0, s36
	s_add_u32 s14, s30, 0x4000
	global_load_lds_dwordx4 v236, s[30:31]
	s_mov_b32 m0, s37
	s_addc_u32 s15, s31, 0
	s_add_i32 s42, s36, 0x4000
	global_load_lds_dwordx4 v240, s[30:31]
	s_mov_b32 m0, s42
	s_add_i32 s43, s36, 0x6000
	global_load_lds_dwordx4 v236, s[14:15]
	s_mov_b32 m0, s43
	v_mov_b32_e32 v239, v0
	global_load_lds_dwordx4 v240, s[14:15]
	v_mov_b32_e32 v243, v0
	v_mov_b32_e32 v237, v0
	v_mov_b32_e32 v241, v0
	s_cmp_eq_u32 s34, 1
	v_lshl_add_u64 v[8:9], s[40:41], 0, v[238:239]
	v_lshl_add_u64 v[6:7], s[40:41], 0, v[242:243]
	v_lshl_add_u64 v[2:3], s[30:31], 0, v[236:237]
	s_cselect_b64 s[14:15], -1, 0
	s_cmp_lg_u32 s34, 1
	v_lshl_add_u64 v[4:5], s[30:31], 0, v[240:241]
	s_cbranch_scc1 .LBB0_683
	s_barrier
; __device__ __forceinline__ float sum_x1(float s) { return s + DPP_MOVF(s, 0xB1); }
; __device__ __forceinline__ void prep_rstd(PG8_LAS unsigned char* lds, const float* ss, int tid, int pm) {
;     ...
;     f32x4 a = p[0] + p[1]; const f32x4 b = p[2] + p[3]; a += b; float t = (a[0] + a[1]) + (a[2] + a[3]);
;     t = sum_x1(t);
;     if (h == 0) RS[row] = __builtin_amdgcn_rsqf(t * (1.0f / 2048.0f) + RMS_EPS);
;     asm volatile("s_waitcnt lgkmcnt(0)" ::: "memory"); __syncthreads();
.LBB0_683:
	s_add_u32 s92, s8, 0x21400000
	s_addc_u32 s93, s9, 0
	s_lshl_b64 s[26:27], s[12:13], 2
	s_add_u32 s96, s4, s26
	s_addc_u32 s97, s5, s27
	s_lshl_b64 s[4:5], s[10:11], 2
	s_add_u32 s44, s6, s4
	s_addc_u32 s45, s7, s5
	v_and_b32_e32 v1, 15, v10
	s_add_u32 s46, s8, 0x2c400000
	v_bfe_u32 v253, v10, 4, 2
	v_lshlrev_b32_e32 v19, 6, v1
	v_lshlrev_b32_e32 v10, 2, v10
	s_addc_u32 s47, s9, 0
	s_and_b32 s4, s2, 3
	v_lshl_or_b32 v19, v253, 4, v19
	s_lshl_b32 s2, s34, 13
	v_and_b32_e32 v10, 32, v10
	s_add_i32 m0, s36, 0x18000
	v_lshl_add_u64 v[8:9], v[8:9], 0, s[60:61]
	v_bitop3_b32 v20, v19, s2, v10 bitop3:0xde
	s_lshl_b32 s50, s4, 5
	s_lshl_b32 s2, s4, 12
	global_load_lds_dwordx4 v[8:9], off
	v_lshl_add_u64 v[6:7], v[6:7], 0, s[60:61]
	s_add_i32 m0, s36, 0x1a000
	s_add_i32 s77, s36, 0x8000
	s_add_i32 s94, s36, 0xa000
	v_bitop3_b32 v251, v19, s2, v10 bitop3:0xde
	global_load_lds_dwordx4 v[6:7], off
	v_lshl_add_u64 v[2:3], v[2:3], 0, s[60:61]
	s_mov_b32 m0, s77
	s_add_u32 s2, s40, 0x80080
	global_load_lds_dwordx4 v[2:3], off
	v_lshl_add_u64 v[2:3], v[4:5], 0, s[60:61]
	s_mov_b32 m0, s94
	s_addc_u32 s3, s41, 0
	global_load_lds_dwordx4 v[2:3], off
	s_add_i32 m0, s36, 0x1c000
	v_lshl_add_u64 v[2:3], s[2:3], 0, v[238:239]
	global_load_lds_dwordx4 v[2:3], off
	v_lshl_add_u64 v[2:3], s[2:3], 0, v[242:243]
	s_add_i32 m0, s36, 0x1e000
	s_waitcnt vmcnt(13)
	v_pk_add_f32 v[206:207], v[206:207], v[210:211]
	v_pk_add_f32 v[204:205], v[204:205], v[208:209]
	v_pk_add_f32 v[220:221], v[214:215], v[218:219]
	v_pk_add_f32 v[222:223], v[212:213], v[216:217]
	v_pk_add_f32 v[206:207], v[206:207], v[220:221]
	v_pk_add_f32 v[204:205], v[204:205], v[222:223]
	v_mbcnt_lo_u32_b32 v226, -1, 0
	v_add_f32_e32 v224, v204, v205
	v_add_f32_e32 v225, v206, v207
	v_mbcnt_hi_u32_b32 v226, -1, v226
	v_add_f32_e32 v224, v224, v225
	v_and_b32_e32 v227, 1, v226
	v_or_b32_e32 v226, s55, v226
	v_mov_b32_dpp v225, v224 quad_perm:[1,0,3,2] row_mask:0xf bank_mask:0xf bound_ctrl:1
	v_cmp_eq_u32_e64 s[2:3], 0, v227
	v_ashrrev_i32_e32 v226, 1, v226
	s_and_saveexec_b64 s[2:3], s[2:3]
	s_cbranch_execz .Lrs_u
	v_add_f32_e32 v224, v224, v225
	v_fmamk_f32 v224, v224, 0x3a000000, v250
	v_rsq_f32_e32 v224, v224
	v_lshl_add_u32 v226, v226, 2, 0
	v_add_u32_e32 v226, 0x22100, v226
	ds_write_b32 v226, v224
.Lrs_u:
	s_or_b64 exec, exec, s[2:3]
	s_cmpk_lt_u32 s20, 0x100
	global_load_lds_dwordx4 v[2:3], off
	s_waitcnt vmcnt(8)
	s_barrier
	s_cselect_b64 s[26:27], -1, 0
	s_and_b32 s2, s20, 0xffffff00
	s_lshl_b32 s3, s4, 6
	s_or_b32 s95, s3, s2
	v_lshlrev_b32_e32 v2, 13, v12
	v_lshlrev_b32_e32 v3, 15, v14
	s_mov_b32 s2, 0xfff80000
	v_and_or_b32 v2, v2, s2, v3
	v_add3_u32 v3, v15, v11, v13
	v_lshl_add_u32 v2, v3, 1, v2
	v_mov_b32_e32 v3, v0
	s_mov_b64 s[4:5], 0x4080
	v_lshl_add_u64 v[244:245], v[2:3], 0, s[4:5]
	v_lshlrev_b32_e32 v2, 13, v16
	v_lshlrev_b32_e32 v3, 15, v17
	s_waitcnt vmcnt(6)
	v_and_or_b32 v2, v2, s2, v3
	v_add_u32_e32 v2, v2, v18
	v_mov_b32_e32 v3, v0
	v_readlane_b32 s2, v255, 32
	s_lshl_b32 s80, s34, 7
	v_lshl_add_u64 v[246:247], v[2:3], 0, s[4:5]
	s_mov_b32 s81, 0
	v_add_u32_e32 v252, 0, v20
	v_readlane_b32 s85, v255, 20
	s_mov_b32 s84, s2
	s_barrier
	v_readlane_b32 s3, v255, 33
	s_branch .LBB0_686
